# NA attention: 32 serialized bias LDS lookups per tile batched; GQA attention: 16-element max reductions as v_max3 trees
# speedup vs baseline: 1.2522x; 1.0133x over previous
; #define MFMA(a, b, c) __builtin_amdgcn_mfma_f32_32x32x16_bf16((a), (b), (c), 0, 0, 0)
; #define GLOAD(t) { const int pos0_ = TILE_POS(t); \
;     rk0 = *(const uint4*)(K + (size_t)(pos0_ + kr0) * ldk + kc0); rk1 = *(const uint4*)(K + (size_t)(pos0_ + kr1) * ldk + kc1); \
;     if (NKC == 3) rk2 = *(const uint4*)(K + (size_t)(pos0_ + kr2) * ldk + kc2); \
;     rv0 = *(const uint4*)(Vt + (size_t)vd0 * SEQA + pos0_ + vk0); rv1 = *(const uint4*)(Vt + (size_t)(vd0 + 32) * SEQA + pos0_ + vk0); }
; #define GLOAD(t) { const int pos0_ = (t) * 64; \
;     rk0 = *(const uint4*)(K + (size_t)(pos0_ + kr0) * ldk + kc0); rk1 = *(const uint4*)(K + (size_t)(pos0_ + kr1) * ldk + kc1); \
;     if (NKC == 3) rk2 = *(const uint4*)(K + (size_t)(pos0_ + kr2) * ldk + kc2); \
;     rv0 = *(const uint4*)(Vt + (size_t)vd0 * SEQA + pos0_ + vk0); rv1 = *(const uint4*)(Vt + (size_t)(vd0 + 32) * SEQA + pos0_ + vk0); }
; template <int DK>
; DI void attn_item2(const u16* __restrict__ Q, int ldq, const u16* __restrict__ K, int ldk, const u16* __restrict__ Vt, int nTiles,
;                    u16* __restrict__ Gp, const u16* __restrict__ Zp, char* smem, int tid) {
;     ...
;   for (int t = 0; t < nTiles; t++) {
;     const int buf = t & 1;
;     if (t + 1 < nTiles) GLOAD(t + 1);
; #pragma unroll
;     for (int kb = 0; kb < 2; kb++) {
;       f32x16 s0, s1;
; #pragma unroll
;       for (int i = 0; i < 16; i++) { s0[i] = 0.f; s1[i] = 0.f; }
; #pragma unroll
;       for (int ks = 0; ks < KS; ks++) {
;         bf16x8 a = *(const bf16x8*)&Ks[buf][kb * 32 + r][ks * 16 + h * 8];
;         s0 = MFMA(a, qf[0][ks], s0);
;         s1 = MFMA(a, qf[1][ks], s1);
;       }
;       bf16x8 pf0[2], pf1[2];
.LBB0_862:
	v_lshl_add_u64 v[14:15], v[198:199], 0, v[204:205]
	s_mov_b32 s8, 0xf240000
	v_add_co_u32_e32 v10, vcc, s8, v14
	s_mov_b32 s8, 0xf284000
	s_nop 0
	v_addc_co_u32_e32 v11, vcc, 0, v15, vcc
	v_add_co_u32_e32 v14, vcc, s8, v14
	v_lshl_add_u64 v[2:3], v[200:201], 0, v[204:205]
	v_lshl_add_u64 v[6:7], v[202:203], 0, v[204:205]
	v_addc_co_u32_e32 v15, vcc, 0, v15, vcc
	global_load_dwordx4 v[2:5], v[2:3], off
	s_and_b32 s3, s2, 1
	global_load_dwordx4 v[6:9], v[6:7], off
	s_mul_i32 s8, s3, 0x2400
	global_load_dwordx4 v[10:13], v[10:11], off offset:128
	v_add_u32_e32 v230, s8, v225
	global_load_dwordx4 v[144:147], v[14:15], off offset:128
	ds_read_b128 v[80:83], v230
	ds_read_b128 v[232:235], v230 offset:32
	s_waitcnt vmcnt(11) lgkmcnt(1)
	v_mfma_f32_32x32x16_bf16 v[96:111], v[80:83], v[132:135], 0
	s_waitcnt vmcnt(7)
	v_mfma_f32_32x32x16_bf16 v[80:95], v[80:83], v[140:143], 0
	s_waitcnt lgkmcnt(0)
	v_mfma_f32_32x32x16_bf16 v[96:111], v[232:235], v[124:127], v[96:111]
	s_waitcnt vmcnt(6)
	v_mfma_f32_32x32x16_bf16 v[80:95], v[232:235], v[136:139], v[80:95]
	ds_read_b128 v[232:235], v230 offset:64
	s_waitcnt lgkmcnt(0)
	v_mfma_f32_32x32x16_bf16 v[96:111], v[232:235], v[120:123], v[96:111]
	s_waitcnt vmcnt(5)
	v_mfma_f32_32x32x16_bf16 v[80:95], v[232:235], v[128:131], v[80:95]
	ds_read_b128 v[232:235], v230 offset:96
	s_waitcnt lgkmcnt(0)
	v_mfma_f32_32x32x16_bf16 v[96:111], v[232:235], v[112:115], v[96:111]
	s_waitcnt vmcnt(4)
	v_mfma_f32_32x32x16_bf16 v[80:95], v[232:235], v[116:119], v[80:95]
	s_nop 9
	v_max3_f32 v14, v96, v97, v98
	v_max3_f32 v15, v99, v100, v101
	v_max3_f32 v231, v102, v103, v104
	v_max3_f32 v232, v105, v106, v107
	v_max3_f32 v233, v108, v109, v110
	v_max3_f32 v14, v14, v15, v231
	v_max3_f32 v232, v232, v233, v111
	v_max_f32_e32 v14, v14, v232
	v_mov_b32_e32 v15, v14
	s_nop 1
	v_permlane32_swap_b32_e32 v14, v15
	v_max_f32_e32 v15, v15, v15
	v_max_f32_e32 v14, v14, v14
	v_max_f32_e32 v14, v14, v15
	v_cmp_gt_f32_e32 vcc, v14, v191
	s_cbranch_vccz .LBB0_864
	v_max_f32_e32 v14, v14, v14
	v_max_f32_e32 v15, v191, v191
	v_max_f32_e32 v15, v15, v14
	v_sub_f32_e32 v14, v191, v15
	v_exp_f32_e32 v14, v14
	v_mov_b32_e32 v191, v15
	v_pk_mul_f32 v[78:79], v[78:79], v[14:15] op_sel_hi:[1,0]
	v_pk_mul_f32 v[76:77], v[76:77], v[14:15] op_sel_hi:[1,0]
	v_pk_mul_f32 v[74:75], v[74:75], v[14:15] op_sel_hi:[1,0]
	v_pk_mul_f32 v[72:73], v[72:73], v[14:15] op_sel_hi:[1,0]
	v_pk_mul_f32 v[70:71], v[70:71], v[14:15] op_sel_hi:[1,0]
	v_pk_mul_f32 v[68:69], v[68:69], v[14:15] op_sel_hi:[1,0]
	v_pk_mul_f32 v[66:67], v[66:67], v[14:15] op_sel_hi:[1,0]
	v_pk_mul_f32 v[64:65], v[64:65], v[14:15] op_sel_hi:[1,0]
	v_pk_mul_f32 v[62:63], v[62:63], v[14:15] op_sel_hi:[1,0]
	v_pk_mul_f32 v[60:61], v[60:61], v[14:15] op_sel_hi:[1,0]
	v_pk_mul_f32 v[58:59], v[58:59], v[14:15] op_sel_hi:[1,0]
	v_pk_mul_f32 v[56:57], v[56:57], v[14:15] op_sel_hi:[1,0]
	v_pk_mul_f32 v[54:55], v[54:55], v[14:15] op_sel_hi:[1,0]
	v_pk_mul_f32 v[52:53], v[52:53], v[14:15] op_sel_hi:[1,0]
	v_pk_mul_f32 v[50:51], v[50:51], v[14:15] op_sel_hi:[1,0]
	v_pk_mul_f32 v[48:49], v[48:49], v[14:15] op_sel_hi:[1,0]
	v_mul_f32_e32 v229, v229, v14
.LBB0_864:
	v_max3_f32 v14, v80, v81, v82
	v_max3_f32 v15, v83, v84, v85
	v_max3_f32 v231, v86, v87, v88
	v_max3_f32 v232, v89, v90, v91
	v_max3_f32 v233, v92, v93, v94
	v_max3_f32 v14, v14, v15, v231
	v_max3_f32 v232, v232, v233, v95
	v_max_f32_e32 v14, v14, v232
	v_mov_b32_e32 v15, v14
	s_nop 1
	v_permlane32_swap_b32_e32 v14, v15
	v_max_f32_e32 v15, v15, v15
	v_max_f32_e32 v14, v14, v14
	v_max_f32_e32 v14, v14, v15
	v_cmp_gt_f32_e32 vcc, v14, v189
	s_cbranch_vccz .LBB0_866
	v_max_f32_e32 v14, v14, v14
	v_max_f32_e32 v15, v189, v189
	v_max_f32_e32 v15, v15, v14
	v_sub_f32_e32 v14, v189, v15
	v_exp_f32_e32 v14, v14
	v_mov_b32_e32 v189, v15
	v_pk_mul_f32 v[46:47], v[46:47], v[14:15] op_sel_hi:[1,0]
	v_pk_mul_f32 v[44:45], v[44:45], v[14:15] op_sel_hi:[1,0]
	v_pk_mul_f32 v[42:43], v[42:43], v[14:15] op_sel_hi:[1,0]
	v_pk_mul_f32 v[40:41], v[40:41], v[14:15] op_sel_hi:[1,0]
	v_pk_mul_f32 v[38:39], v[38:39], v[14:15] op_sel_hi:[1,0]
	v_pk_mul_f32 v[36:37], v[36:37], v[14:15] op_sel_hi:[1,0]
	v_pk_mul_f32 v[34:35], v[34:35], v[14:15] op_sel_hi:[1,0]
	v_pk_mul_f32 v[32:33], v[32:33], v[14:15] op_sel_hi:[1,0]
	v_pk_mul_f32 v[30:31], v[30:31], v[14:15] op_sel_hi:[1,0]
	v_pk_mul_f32 v[28:29], v[28:29], v[14:15] op_sel_hi:[1,0]
	v_pk_mul_f32 v[26:27], v[26:27], v[14:15] op_sel_hi:[1,0]
	v_pk_mul_f32 v[24:25], v[24:25], v[14:15] op_sel_hi:[1,0]
	v_pk_mul_f32 v[22:23], v[22:23], v[14:15] op_sel_hi:[1,0]
	v_pk_mul_f32 v[20:21], v[20:21], v[14:15] op_sel_hi:[1,0]
	v_pk_mul_f32 v[18:19], v[18:19], v[14:15] op_sel_hi:[1,0]
	v_pk_mul_f32 v[16:17], v[16:17], v[14:15] op_sel_hi:[1,0]
	v_mul_f32_e32 v0, v0, v14
; #define MFMA(a, b, c) __builtin_amdgcn_mfma_f32_32x32x16_bf16((a), (b), (c), 0, 0, 0)
; template <int DK>
; DI void attn_item2(const u16* __restrict__ Q, int ldq, const u16* __restrict__ K, int ldk, const u16* __restrict__ Vt, int nTiles,
;                    u16* __restrict__ Gp, const u16* __restrict__ Zp, char* smem, int tid) {
;     ...
;     for (int kb = 0; kb < 2; kb++) {
;       f32x16 s0, s1;
; #pragma unroll
;       for (int i = 0; i < 16; i++) { s0[i] = 0.f; s1[i] = 0.f; }
; #pragma unroll
;       for (int ks = 0; ks < KS; ks++) {
;         bf16x8 a = *(const bf16x8*)&Ks[buf][kb * 32 + r][ks * 16 + h * 8];
;         s0 = MFMA(a, qf[0][ks], s0);
;         s1 = MFMA(a, qf[1][ks], s1);
;       }
;       bf16x8 pf0[2], pf1[2];
;     ...
;       SOFTMAX_STEP(s0, m_run0, l_run0, o[0], pf0)
;       SOFTMAX_STEP(s1, m_run1, l_run1, o[1], pf1)
;     ...
; #pragma unroll
;       for (int db = 0; db < 2; db++)
; #pragma unroll
;         for (int sx = 0; sx < 2; sx++) {
;           const u16* vp = &Vs[buf][db * 32 + r][32 * kb + 16 * sx + 4 * h];
;           uint2 lo = *(const uint2*)vp, hi = *(const uint2*)(vp + 8);
;           uint4 u; u.x = lo.x; u.y = lo.y; u.z = hi.x; u.w = hi.y;
;           const bf16x8 a = __builtin_bit_cast(bf16x8, u);
;           o[0][db] = MFMA(a, pf0[sx], o[0][db]);
;           o[1][db] = MFMA(a, pf1[sx], o[1][db]);
;         }
.LBB0_866:
	v_sub_f32_e32 v14, v96, v191
	v_exp_f32_e32 v14, v14
	v_sub_f32_e32 v96, v97, v191
	v_exp_f32_e32 v96, v96
	v_sub_f32_e32 v97, v98, v191
	v_exp_f32_e32 v97, v97
	v_sub_f32_e32 v98, v99, v191
	v_exp_f32_e32 v98, v98
	v_sub_f32_e32 v99, v100, v191
	v_add_f32_e32 v15, 0, v14
	v_exp_f32_e32 v99, v99
	v_sub_f32_e32 v100, v101, v191
	v_add_f32_e32 v15, v96, v15
	v_exp_f32_e32 v231, v100
	v_sub_f32_e32 v100, v102, v191
	v_add_f32_e32 v15, v97, v15
	v_exp_f32_e32 v232, v100
	v_sub_f32_e32 v100, v103, v191
	v_add_f32_e32 v15, v98, v15
	v_exp_f32_e32 v103, v100
	v_sub_f32_e32 v100, v104, v191
	v_add_f32_e32 v15, v99, v15
	v_exp_f32_e32 v104, v100
	v_sub_f32_e32 v100, v105, v191
	v_add_f32_e32 v15, v231, v15
	v_exp_f32_e32 v105, v100
	v_sub_f32_e32 v100, v106, v191
	v_add_f32_e32 v15, v232, v15
	v_exp_f32_e32 v106, v100
	v_sub_f32_e32 v100, v107, v191
	v_add_f32_e32 v15, v103, v15
	v_exp_f32_e32 v107, v100
	v_sub_f32_e32 v100, v108, v191
	v_add_f32_e32 v15, v104, v15
	v_exp_f32_e32 v108, v100
	v_sub_f32_e32 v100, v109, v191
	v_add_f32_e32 v15, v105, v15
	v_exp_f32_e32 v109, v100
	v_sub_f32_e32 v100, v110, v191
	v_add_f32_e32 v15, v106, v15
	v_exp_f32_e32 v110, v100
	v_sub_f32_e32 v100, v111, v191
	v_add_f32_e32 v15, v107, v15
	v_exp_f32_e32 v111, v100
	v_add_f32_e32 v15, v108, v15
	v_add_f32_e32 v15, v109, v15
	v_add_f32_e32 v15, v110, v15
	v_add_f32_e32 v15, v111, v15
	v_add_f32_e32 v229, v229, v15
	v_sub_f32_e32 v15, v80, v189
	v_cvt_pk_bf16_f32 v102, v99, v231
	v_exp_f32_e32 v231, v15
	v_sub_f32_e32 v15, v81, v189
	v_cvt_pk_bf16_f32 v103, v232, v103
	v_exp_f32_e32 v232, v15
	v_sub_f32_e32 v15, v82, v189
	v_exp_f32_e32 v233, v15
	v_sub_f32_e32 v15, v83, v189
	v_exp_f32_e32 v234, v15
	v_sub_f32_e32 v15, v84, v189
	v_exp_f32_e32 v235, v15
	v_sub_f32_e32 v15, v85, v189
	v_exp_f32_e32 v236, v15
	v_sub_f32_e32 v15, v86, v189
	v_exp_f32_e32 v237, v15
	v_sub_f32_e32 v15, v87, v189
	v_exp_f32_e32 v238, v15
	v_sub_f32_e32 v15, v88, v189
	v_exp_f32_e32 v239, v15
	v_sub_f32_e32 v15, v89, v189
	v_exp_f32_e32 v240, v15
	v_sub_f32_e32 v15, v90, v189
	v_exp_f32_e32 v241, v15
	v_sub_f32_e32 v15, v91, v189
	v_exp_f32_e32 v242, v15
	v_sub_f32_e32 v15, v92, v189
	v_exp_f32_e32 v243, v15
	v_sub_f32_e32 v15, v93, v189
	s_mul_i32 s8, s3, 0x2200
	v_exp_f32_e32 v244, v15
	v_sub_f32_e32 v15, v94, v189
	v_cvt_pk_bf16_f32 v100, v14, v96
	v_add_u32_e32 v14, s8, v226
	v_exp_f32_e32 v245, v15
	v_sub_f32_e32 v15, v95, v189
	v_exp_f32_e32 v246, v15
	v_add_u32_e32 v15, 0x4800, v14
	ds_read2_b64 v[88:91], v15 offset1:2
	ds_read2_b64 v[92:95], v15 offset0:4 offset1:6
	v_cvt_pk_bf16_f32 v101, v97, v98
	v_cvt_pk_bf16_f32 v84, v231, v232
	v_cvt_pk_bf16_f32 v85, v233, v234
	v_cvt_pk_bf16_f32 v86, v235, v236
	v_cvt_pk_bf16_f32 v87, v237, v238
	v_add_u32_e32 v14, 0x5800, v14
	s_waitcnt lgkmcnt(1)
	v_mfma_f32_32x32x16_bf16 v[64:79], v[88:91], v[100:103], v[64:79]
	v_cvt_pk_bf16_f32 v80, v239, v240
	v_cvt_pk_bf16_f32 v81, v241, v242
	v_cvt_pk_bf16_f32 v82, v243, v244
	v_cvt_pk_bf16_f32 v83, v245, v246
	v_cvt_pk_bf16_f32 v96, v104, v105
	v_cvt_pk_bf16_f32 v97, v106, v107
	v_cvt_pk_bf16_f32 v98, v108, v109
	v_mfma_f32_32x32x16_bf16 v[32:47], v[88:91], v[84:87], v[32:47]
	ds_read2_b64 v[88:91], v14 offset0:32 offset1:34
	v_cvt_pk_bf16_f32 v99, v110, v111
	s_waitcnt lgkmcnt(0)
	v_mfma_f32_32x32x16_bf16 v[16:31], v[88:91], v[84:87], v[16:31]
	ds_read2_b64 v[84:87], v14 offset0:36 offset1:38
	v_mfma_f32_32x32x16_bf16 v[48:63], v[88:91], v[100:103], v[48:63]
	v_mfma_f32_32x32x16_bf16 v[32:47], v[92:95], v[80:83], v[32:47]
	s_waitcnt lgkmcnt(0)
	v_mfma_f32_32x32x16_bf16 v[16:31], v[84:87], v[80:83], v[16:31]
	ds_read_b128 v[80:83], v230 offset:4608
	ds_read_b128 v[248:251], v230 offset:4640
	v_mfma_f32_32x32x16_bf16 v[64:79], v[92:95], v[96:99], v[64:79]
	v_mfma_f32_32x32x16_bf16 v[48:63], v[84:87], v[96:99], v[48:63]
	s_waitcnt lgkmcnt(1)
	v_mfma_f32_32x32x16_bf16 v[96:111], v[80:83], v[132:135], 0
	v_mfma_f32_32x32x16_bf16 v[80:95], v[80:83], v[140:143], 0
	s_waitcnt lgkmcnt(0)
	v_mfma_f32_32x32x16_bf16 v[96:111], v[248:251], v[124:127], v[96:111]
	v_mfma_f32_32x32x16_bf16 v[80:95], v[248:251], v[136:139], v[80:95]
	ds_read_b128 v[248:251], v230 offset:4672
	s_waitcnt lgkmcnt(0)
	v_mfma_f32_32x32x16_bf16 v[96:111], v[248:251], v[120:123], v[96:111]
	v_mfma_f32_32x32x16_bf16 v[80:95], v[248:251], v[128:131], v[80:95]
	ds_read_b128 v[248:251], v230 offset:4704
	s_waitcnt lgkmcnt(0)
	v_mfma_f32_32x32x16_bf16 v[96:111], v[248:251], v[112:115], v[96:111]
	v_mfma_f32_32x32x16_bf16 v[80:95], v[248:251], v[116:119], v[80:95]
	s_nop 10
	v_max3_f32 v230, v96, v97, v98
	v_max3_f32 v247, v99, v100, v101
	v_max3_f32 v248, v102, v103, v104
	v_max3_f32 v249, v105, v106, v107
	v_max3_f32 v250, v108, v109, v110
	v_max3_f32 v230, v230, v247, v248
	v_max3_f32 v249, v249, v250, v111
	v_max_f32_e32 v230, v230, v249
	v_mov_b32_e32 v247, v230
	s_nop 1
	v_permlane32_swap_b32_e32 v230, v247
	v_max_f32_e32 v247, v247, v247
	v_max_f32_e32 v230, v230, v230
	v_max_f32_e32 v230, v230, v247
	v_cmp_gt_f32_e32 vcc, v230, v191
	s_cbranch_vccz .LBB0_868
	v_max_f32_e32 v230, v230, v230
	v_max_f32_e32 v247, v191, v191
	v_max_f32_e32 v247, v247, v230
	v_sub_f32_e32 v191, v191, v247
	v_exp_f32_e32 v230, v191
	v_mov_b32_e32 v191, v247
	v_pk_mul_f32 v[78:79], v[78:79], v[230:231] op_sel_hi:[1,0]
	v_pk_mul_f32 v[76:77], v[76:77], v[230:231] op_sel_hi:[1,0]
	v_pk_mul_f32 v[74:75], v[74:75], v[230:231] op_sel_hi:[1,0]
	v_pk_mul_f32 v[72:73], v[72:73], v[230:231] op_sel_hi:[1,0]
	v_pk_mul_f32 v[70:71], v[70:71], v[230:231] op_sel_hi:[1,0]
	v_pk_mul_f32 v[68:69], v[68:69], v[230:231] op_sel_hi:[1,0]
	v_pk_mul_f32 v[66:67], v[66:67], v[230:231] op_sel_hi:[1,0]
	v_pk_mul_f32 v[64:65], v[64:65], v[230:231] op_sel_hi:[1,0]
	v_pk_mul_f32 v[62:63], v[62:63], v[230:231] op_sel_hi:[1,0]
	v_pk_mul_f32 v[60:61], v[60:61], v[230:231] op_sel_hi:[1,0]
	v_pk_mul_f32 v[58:59], v[58:59], v[230:231] op_sel_hi:[1,0]
	v_pk_mul_f32 v[56:57], v[56:57], v[230:231] op_sel_hi:[1,0]
	v_pk_mul_f32 v[54:55], v[54:55], v[230:231] op_sel_hi:[1,0]
	v_pk_mul_f32 v[52:53], v[52:53], v[230:231] op_sel_hi:[1,0]
	v_pk_mul_f32 v[50:51], v[50:51], v[230:231] op_sel_hi:[1,0]
	v_pk_mul_f32 v[48:49], v[48:49], v[230:231] op_sel_hi:[1,0]
	v_mul_f32_e32 v229, v229, v230
.LBB0_868:
	v_add_f32_e32 v230, 0, v231
	v_add_f32_e32 v230, v232, v230
	v_add_f32_e32 v230, v233, v230
	v_add_f32_e32 v230, v234, v230
	v_add_f32_e32 v230, v235, v230
	v_add_f32_e32 v230, v236, v230
	v_add_f32_e32 v230, v237, v230
	v_add_f32_e32 v230, v238, v230
	v_add_f32_e32 v230, v239, v230
	v_add_f32_e32 v230, v240, v230
	v_add_f32_e32 v230, v241, v230
	v_add_f32_e32 v230, v242, v230
	v_add_f32_e32 v230, v243, v230
	v_add_f32_e32 v230, v244, v230
	v_add_f32_e32 v230, v245, v230
	v_add_f32_e32 v230, v246, v230
	v_add_f32_e32 v0, v0, v230
	v_max3_f32 v230, v80, v81, v82
	v_max3_f32 v231, v83, v84, v85
	v_max3_f32 v232, v86, v87, v88
	v_max3_f32 v233, v89, v90, v91
	v_max3_f32 v234, v92, v93, v94
	v_max3_f32 v230, v230, v231, v232
	v_max3_f32 v233, v233, v234, v95
	v_max_f32_e32 v230, v230, v233
	v_mov_b32_e32 v231, v230
	s_nop 1
	v_permlane32_swap_b32_e32 v230, v231
	v_max_f32_e32 v231, v231, v231
	v_max_f32_e32 v230, v230, v230
	v_max_f32_e32 v230, v230, v231
	v_cmp_gt_f32_e32 vcc, v230, v189
	s_cbranch_vccz .LBB0_861
	v_max_f32_e32 v230, v230, v230
	v_max_f32_e32 v231, v189, v189
	v_max_f32_e32 v231, v231, v230
	v_sub_f32_e32 v189, v189, v231
	v_exp_f32_e32 v230, v189
	v_mov_b32_e32 v189, v231
	v_pk_mul_f32 v[46:47], v[46:47], v[230:231] op_sel_hi:[1,0]
	v_pk_mul_f32 v[44:45], v[44:45], v[230:231] op_sel_hi:[1,0]
	v_pk_mul_f32 v[42:43], v[42:43], v[230:231] op_sel_hi:[1,0]
	v_pk_mul_f32 v[40:41], v[40:41], v[230:231] op_sel_hi:[1,0]
	v_pk_mul_f32 v[38:39], v[38:39], v[230:231] op_sel_hi:[1,0]
	v_pk_mul_f32 v[36:37], v[36:37], v[230:231] op_sel_hi:[1,0]
	v_pk_mul_f32 v[34:35], v[34:35], v[230:231] op_sel_hi:[1,0]
	v_pk_mul_f32 v[32:33], v[32:33], v[230:231] op_sel_hi:[1,0]
	v_pk_mul_f32 v[30:31], v[30:31], v[230:231] op_sel_hi:[1,0]
	v_pk_mul_f32 v[28:29], v[28:29], v[230:231] op_sel_hi:[1,0]
	v_pk_mul_f32 v[26:27], v[26:27], v[230:231] op_sel_hi:[1,0]
	v_pk_mul_f32 v[24:25], v[24:25], v[230:231] op_sel_hi:[1,0]
	v_pk_mul_f32 v[22:23], v[22:23], v[230:231] op_sel_hi:[1,0]
	v_pk_mul_f32 v[20:21], v[20:21], v[230:231] op_sel_hi:[1,0]
	v_pk_mul_f32 v[18:19], v[18:19], v[230:231] op_sel_hi:[1,0]
	v_pk_mul_f32 v[16:17], v[16:17], v[230:231] op_sel_hi:[1,0]
	v_mul_f32_e32 v0, v0, v230
	s_branch .LBB0_861
.LBB0_870:
	s_or_b64 exec, exec, s[6:7]
	v_and_b32_e32 v10, 1, v193
	v_mad_u32_u24 v14, v10, s28, v225
	ds_read_b128 v[2:5], v14
	ds_read_b128 v[6:9], v14 offset:32
	s_waitcnt lgkmcnt(1)
	v_mfma_f32_32x32x16_bf16 v[96:111], v[2:5], v[132:135], 0
	v_mfma_f32_32x32x16_bf16 v[80:95], v[2:5], v[140:143], 0
	ds_read_b128 v[2:5], v14 offset:64
	s_waitcnt lgkmcnt(1)
	v_mfma_f32_32x32x16_bf16 v[96:111], v[6:9], v[124:127], v[96:111]
	v_mfma_f32_32x32x16_bf16 v[80:95], v[6:9], v[136:139], v[80:95]
	s_waitcnt lgkmcnt(0)
	v_mfma_f32_32x32x16_bf16 v[96:111], v[2:5], v[120:123], v[96:111]
	v_mfma_f32_32x32x16_bf16 v[80:95], v[2:5], v[128:131], v[80:95]
	ds_read_b128 v[2:5], v14 offset:96
	s_waitcnt lgkmcnt(0)
	v_mfma_f32_32x32x16_bf16 v[96:111], v[2:5], v[112:115], v[96:111]
	v_mfma_f32_32x32x16_bf16 v[80:95], v[2:5], v[116:119], v[80:95]
	s_nop 10
	v_max3_f32 v2, v96, v97, v98
	v_max3_f32 v3, v99, v100, v101
	v_max3_f32 v4, v102, v103, v104
	v_max3_f32 v5, v105, v106, v107
	v_max3_f32 v6, v108, v109, v110
	v_max3_f32 v2, v2, v3, v4
	v_max3_f32 v5, v5, v6, v111
	v_max_f32_e32 v2, v2, v5
	v_mov_b32_e32 v3, v2
	s_nop 1
	v_permlane32_swap_b32_e32 v2, v3
	v_max_f32_e32 v3, v3, v3
	v_max_f32_e32 v2, v2, v2
	v_max_f32_e32 v2, v2, v3
	v_cmp_gt_f32_e32 vcc, v2, v191
	s_cbranch_vccz .LBB0_872
	v_max_f32_e32 v2, v2, v2
	v_max_f32_e32 v3, v191, v191
	v_max_f32_e32 v3, v3, v2
	v_sub_f32_e32 v2, v191, v3
	v_exp_f32_e32 v2, v2
	v_mov_b32_e32 v191, v3
	v_pk_mul_f32 v[78:79], v[78:79], v[2:3] op_sel_hi:[1,0]
	v_pk_mul_f32 v[76:77], v[76:77], v[2:3] op_sel_hi:[1,0]
	v_pk_mul_f32 v[74:75], v[74:75], v[2:3] op_sel_hi:[1,0]
	v_pk_mul_f32 v[72:73], v[72:73], v[2:3] op_sel_hi:[1,0]
	v_pk_mul_f32 v[70:71], v[70:71], v[2:3] op_sel_hi:[1,0]
	v_pk_mul_f32 v[68:69], v[68:69], v[2:3] op_sel_hi:[1,0]
	v_pk_mul_f32 v[66:67], v[66:67], v[2:3] op_sel_hi:[1,0]
	v_pk_mul_f32 v[64:65], v[64:65], v[2:3] op_sel_hi:[1,0]
	v_pk_mul_f32 v[62:63], v[62:63], v[2:3] op_sel_hi:[1,0]
	v_pk_mul_f32 v[60:61], v[60:61], v[2:3] op_sel_hi:[1,0]
	v_pk_mul_f32 v[58:59], v[58:59], v[2:3] op_sel_hi:[1,0]
	v_pk_mul_f32 v[56:57], v[56:57], v[2:3] op_sel_hi:[1,0]
	v_pk_mul_f32 v[54:55], v[54:55], v[2:3] op_sel_hi:[1,0]
	v_pk_mul_f32 v[52:53], v[52:53], v[2:3] op_sel_hi:[1,0]
	v_pk_mul_f32 v[50:51], v[50:51], v[2:3] op_sel_hi:[1,0]
	v_pk_mul_f32 v[48:49], v[48:49], v[2:3] op_sel_hi:[1,0]
	v_mul_f32_e32 v229, v229, v2
.LBB0_872:
	v_max3_f32 v2, v80, v81, v82
	v_max3_f32 v3, v83, v84, v85
	v_max3_f32 v4, v86, v87, v88
	v_max3_f32 v5, v89, v90, v91
	v_max3_f32 v6, v92, v93, v94
	v_max3_f32 v2, v2, v3, v4
	v_max3_f32 v5, v5, v6, v95
	v_max_f32_e32 v2, v2, v5
	v_mov_b32_e32 v3, v2
	s_nop 1
	v_permlane32_swap_b32_e32 v2, v3
	v_max_f32_e32 v3, v3, v3
	v_max_f32_e32 v2, v2, v2
	v_max_f32_e32 v2, v2, v3
	v_cmp_gt_f32_e32 vcc, v2, v189
	s_cbranch_vccz .LBB0_874
	v_max_f32_e32 v2, v2, v2
	v_max_f32_e32 v3, v189, v189
	v_max_f32_e32 v3, v3, v2
	v_sub_f32_e32 v2, v189, v3
	v_exp_f32_e32 v2, v2
	v_mov_b32_e32 v189, v3
	v_pk_mul_f32 v[46:47], v[46:47], v[2:3] op_sel_hi:[1,0]
	v_pk_mul_f32 v[44:45], v[44:45], v[2:3] op_sel_hi:[1,0]
	v_pk_mul_f32 v[42:43], v[42:43], v[2:3] op_sel_hi:[1,0]
	v_pk_mul_f32 v[40:41], v[40:41], v[2:3] op_sel_hi:[1,0]
	v_pk_mul_f32 v[38:39], v[38:39], v[2:3] op_sel_hi:[1,0]
	v_pk_mul_f32 v[36:37], v[36:37], v[2:3] op_sel_hi:[1,0]
	v_pk_mul_f32 v[34:35], v[34:35], v[2:3] op_sel_hi:[1,0]
	v_pk_mul_f32 v[32:33], v[32:33], v[2:3] op_sel_hi:[1,0]
	v_pk_mul_f32 v[30:31], v[30:31], v[2:3] op_sel_hi:[1,0]
	v_pk_mul_f32 v[28:29], v[28:29], v[2:3] op_sel_hi:[1,0]
	v_pk_mul_f32 v[26:27], v[26:27], v[2:3] op_sel_hi:[1,0]
	v_pk_mul_f32 v[24:25], v[24:25], v[2:3] op_sel_hi:[1,0]
	v_pk_mul_f32 v[22:23], v[22:23], v[2:3] op_sel_hi:[1,0]
	v_pk_mul_f32 v[20:21], v[20:21], v[2:3] op_sel_hi:[1,0]
	v_pk_mul_f32 v[18:19], v[18:19], v[2:3] op_sel_hi:[1,0]
	v_pk_mul_f32 v[16:17], v[16:17], v[2:3] op_sel_hi:[1,0]
	v_mul_f32_e32 v0, v0, v2
; #define MFMA(a, b, c) __builtin_amdgcn_mfma_f32_32x32x16_bf16((a), (b), (c), 0, 0, 0)
; template <int DK>
; DI void attn_item2(const u16* __restrict__ Q, int ldq, const u16* __restrict__ K, int ldk, const u16* __restrict__ Vt, int nTiles,
;                    u16* __restrict__ Gp, const u16* __restrict__ Zp, char* smem, int tid) {
;     ...
;     for (int kb = 0; kb < 2; kb++) {
;       f32x16 s0, s1;
; #pragma unroll
;       for (int i = 0; i < 16; i++) { s0[i] = 0.f; s1[i] = 0.f; }
; #pragma unroll
;       for (int ks = 0; ks < KS; ks++) {
;         bf16x8 a = *(const bf16x8*)&Ks[buf][kb * 32 + r][ks * 16 + h * 8];
;         s0 = MFMA(a, qf[0][ks], s0);
;         s1 = MFMA(a, qf[1][ks], s1);
;       }
;       bf16x8 pf0[2], pf1[2];
;     ...
;       SOFTMAX_STEP(s0, m_run0, l_run0, o[0], pf0)
;       SOFTMAX_STEP(s1, m_run1, l_run1, o[1], pf1)
;     ...
; #pragma unroll
;       for (int db = 0; db < 2; db++)
; #pragma unroll
;         for (int sx = 0; sx < 2; sx++) {
;           const u16* vp = &Vs[buf][db * 32 + r][32 * kb + 16 * sx + 4 * h];
;           uint2 lo = *(const uint2*)vp, hi = *(const uint2*)(vp + 8);
;           uint4 u; u.x = lo.x; u.y = lo.y; u.z = hi.x; u.w = hi.y;
;           const bf16x8 a = __builtin_bit_cast(bf16x8, u);
;           o[0][db] = MFMA(a, pf0[sx], o[0][db]);
;           o[1][db] = MFMA(a, pf1[sx], o[1][db]);
;         }
.LBB0_874:
	v_sub_f32_e32 v2, v96, v191
	v_exp_f32_e32 v2, v2
	v_sub_f32_e32 v4, v97, v191
	v_exp_f32_e32 v4, v4
	v_sub_f32_e32 v5, v98, v191
	v_exp_f32_e32 v5, v5
	v_sub_f32_e32 v6, v99, v191
	v_exp_f32_e32 v7, v6
	v_sub_f32_e32 v6, v100, v191
	v_add_f32_e32 v3, 0, v2
	v_exp_f32_e32 v8, v6
	v_sub_f32_e32 v6, v101, v191
	v_add_f32_e32 v3, v4, v3
	v_exp_f32_e32 v9, v6
	v_sub_f32_e32 v6, v102, v191
	v_add_f32_e32 v3, v5, v3
	v_exp_f32_e32 v11, v6
	v_sub_f32_e32 v6, v103, v191
	v_add_f32_e32 v3, v7, v3
	v_exp_f32_e32 v12, v6
	v_sub_f32_e32 v6, v104, v191
	v_add_f32_e32 v3, v8, v3
	v_exp_f32_e32 v13, v6
	v_sub_f32_e32 v6, v105, v191
	v_add_f32_e32 v3, v9, v3
	v_exp_f32_e32 v15, v6
	v_sub_f32_e32 v6, v106, v191
	v_add_f32_e32 v3, v11, v3
	v_exp_f32_e32 v96, v6
	v_sub_f32_e32 v6, v107, v191
	v_add_f32_e32 v3, v12, v3
	v_exp_f32_e32 v97, v6
	v_sub_f32_e32 v6, v108, v191
	v_add_f32_e32 v3, v13, v3
	v_exp_f32_e32 v98, v6
	v_sub_f32_e32 v6, v109, v191
	v_add_f32_e32 v3, v15, v3
	v_exp_f32_e32 v99, v6
	v_sub_f32_e32 v6, v110, v191
	v_add_f32_e32 v3, v96, v3
	v_exp_f32_e32 v100, v6
	v_sub_f32_e32 v6, v111, v191
	v_add_f32_e32 v3, v97, v3
	v_exp_f32_e32 v101, v6
	v_add_f32_e32 v3, v98, v3
	v_add_f32_e32 v3, v99, v3
	v_add_f32_e32 v3, v100, v3
	v_add_f32_e32 v102, v101, v3
	v_cvt_pk_bf16_f32 v3, v96, v97
	v_mad_u32_u24 v96, v10, s23, v226
	v_sub_f32_e32 v10, v80, v189
	v_cvt_pk_bf16_f32 v6, v2, v4
	v_cvt_pk_bf16_f32 v2, v13, v15
	v_exp_f32_e32 v15, v10
	v_sub_f32_e32 v10, v81, v189
	v_exp_f32_e32 v147, v10
	v_sub_f32_e32 v10, v82, v189
	v_exp_f32_e32 v193, v10
	v_sub_f32_e32 v10, v83, v189
	v_exp_f32_e32 v198, v10
	v_sub_f32_e32 v10, v84, v189
	v_exp_f32_e32 v199, v10
	v_sub_f32_e32 v10, v85, v189
	v_exp_f32_e32 v200, v10
	v_sub_f32_e32 v10, v86, v189
	v_exp_f32_e32 v201, v10
	v_sub_f32_e32 v10, v87, v189
	v_exp_f32_e32 v202, v10
	v_sub_f32_e32 v10, v88, v189
	v_exp_f32_e32 v203, v10
	v_sub_f32_e32 v10, v89, v189
	v_exp_f32_e32 v204, v10
	v_sub_f32_e32 v10, v90, v189
	v_add_u32_e32 v146, 0x4800, v96
	v_exp_f32_e32 v205, v10
	v_sub_f32_e32 v10, v91, v189
	ds_read2_b64 v[84:87], v146 offset1:2
	ds_read2_b64 v[88:91], v146 offset0:4 offset1:6
	v_cvt_pk_bf16_f32 v7, v5, v7
	v_cvt_pk_bf16_f32 v8, v8, v9
	v_cvt_pk_bf16_f32 v9, v11, v12
	v_cvt_pk_bf16_f32 v80, v15, v147
	v_cvt_pk_bf16_f32 v81, v193, v198
	v_cvt_pk_bf16_f32 v82, v199, v200
	v_cvt_pk_bf16_f32 v83, v201, v202
	v_add_u32_e32 v145, 0x5800, v96
	s_waitcnt lgkmcnt(1)
	v_mfma_f32_32x32x16_bf16 v[64:79], v[84:87], v[6:9], v[64:79]
	v_add_f32_e32 v144, v229, v102
	v_exp_f32_e32 v229, v10
	v_sub_f32_e32 v10, v92, v189
	v_exp_f32_e32 v230, v10
	v_sub_f32_e32 v10, v93, v189
	v_exp_f32_e32 v231, v10
	v_sub_f32_e32 v10, v94, v189
	v_mfma_f32_32x32x16_bf16 v[32:47], v[84:87], v[80:83], v[32:47]
	ds_read2_b64 v[84:87], v145 offset0:32 offset1:34
	v_exp_f32_e32 v232, v10
	v_sub_f32_e32 v10, v95, v189
	v_exp_f32_e32 v233, v10
	v_cvt_pk_bf16_f32 v4, v98, v99
	v_cvt_pk_bf16_f32 v5, v100, v101
	v_cvt_pk_bf16_f32 v10, v203, v204
	s_waitcnt lgkmcnt(0)
	v_mfma_f32_32x32x16_bf16 v[48:63], v[84:87], v[6:9], v[48:63]
	ds_read2_b64 v[6:9], v145 offset0:36 offset1:38
	v_cvt_pk_bf16_f32 v11, v205, v229
	v_cvt_pk_bf16_f32 v12, v230, v231
	v_cvt_pk_bf16_f32 v13, v232, v233
	v_mfma_f32_32x32x16_bf16 v[16:31], v[84:87], v[80:83], v[16:31]
	v_mfma_f32_32x32x16_bf16 v[64:79], v[88:91], v[2:5], v[64:79]
	s_waitcnt lgkmcnt(0)
	v_mfma_f32_32x32x16_bf16 v[48:63], v[6:9], v[2:5], v[48:63]
	v_mfma_f32_32x32x16_bf16 v[16:31], v[6:9], v[10:13], v[16:31]
	ds_read_b128 v[2:5], v14 offset:4608
	ds_read_b128 v[6:9], v14 offset:4640
	v_mfma_f32_32x32x16_bf16 v[32:47], v[88:91], v[10:13], v[32:47]
	s_waitcnt lgkmcnt(1)
	v_mfma_f32_32x32x16_bf16 v[96:111], v[2:5], v[132:135], 0
	v_mfma_f32_32x32x16_bf16 v[80:95], v[2:5], v[140:143], 0
	ds_read_b128 v[2:5], v14 offset:4672
	s_waitcnt lgkmcnt(1)
	v_mfma_f32_32x32x16_bf16 v[96:111], v[6:9], v[124:127], v[96:111]
	v_mfma_f32_32x32x16_bf16 v[80:95], v[6:9], v[136:139], v[80:95]
	s_waitcnt lgkmcnt(0)
	v_mfma_f32_32x32x16_bf16 v[96:111], v[2:5], v[120:123], v[96:111]
	v_mfma_f32_32x32x16_bf16 v[80:95], v[2:5], v[128:131], v[80:95]
	ds_read_b128 v[2:5], v14 offset:4704
	s_waitcnt lgkmcnt(0)
	v_mfma_f32_32x32x16_bf16 v[96:111], v[2:5], v[112:115], v[96:111]
	v_mfma_f32_32x32x16_bf16 v[80:95], v[2:5], v[116:119], v[80:95]
	s_nop 10
	v_max3_f32 v2, v96, v97, v98
	v_max3_f32 v3, v99, v100, v101
	v_max3_f32 v4, v102, v103, v104
	v_max3_f32 v5, v105, v106, v107
	v_max3_f32 v6, v108, v109, v110
	v_max3_f32 v2, v2, v3, v4
	v_max3_f32 v5, v5, v6, v111
	v_max_f32_e32 v2, v2, v5
	v_mov_b32_e32 v3, v2
	s_nop 1
	v_permlane32_swap_b32_e32 v2, v3
	v_max_f32_e32 v3, v3, v3
	v_max_f32_e32 v2, v2, v2
	v_max_f32_e32 v2, v2, v3
	v_cmp_gt_f32_e32 vcc, v2, v191
	s_cbranch_vccz .LBB0_876
	v_max_f32_e32 v2, v2, v2
	v_max_f32_e32 v3, v191, v191
	v_max_f32_e32 v3, v3, v2
	v_sub_f32_e32 v2, v191, v3
	v_exp_f32_e32 v2, v2
	v_mov_b32_e32 v191, v3
	v_pk_mul_f32 v[78:79], v[78:79], v[2:3] op_sel_hi:[1,0]
	v_pk_mul_f32 v[76:77], v[76:77], v[2:3] op_sel_hi:[1,0]
	v_pk_mul_f32 v[74:75], v[74:75], v[2:3] op_sel_hi:[1,0]
	v_pk_mul_f32 v[72:73], v[72:73], v[2:3] op_sel_hi:[1,0]
	v_pk_mul_f32 v[70:71], v[70:71], v[2:3] op_sel_hi:[1,0]
	v_pk_mul_f32 v[68:69], v[68:69], v[2:3] op_sel_hi:[1,0]
	v_pk_mul_f32 v[66:67], v[66:67], v[2:3] op_sel_hi:[1,0]
	v_pk_mul_f32 v[64:65], v[64:65], v[2:3] op_sel_hi:[1,0]
	v_pk_mul_f32 v[62:63], v[62:63], v[2:3] op_sel_hi:[1,0]
	v_pk_mul_f32 v[60:61], v[60:61], v[2:3] op_sel_hi:[1,0]
	v_pk_mul_f32 v[58:59], v[58:59], v[2:3] op_sel_hi:[1,0]
	v_pk_mul_f32 v[56:57], v[56:57], v[2:3] op_sel_hi:[1,0]
	v_pk_mul_f32 v[54:55], v[54:55], v[2:3] op_sel_hi:[1,0]
	v_pk_mul_f32 v[52:53], v[52:53], v[2:3] op_sel_hi:[1,0]
	v_pk_mul_f32 v[50:51], v[50:51], v[2:3] op_sel_hi:[1,0]
	v_pk_mul_f32 v[48:49], v[48:49], v[2:3] op_sel_hi:[1,0]
	v_mul_f32_e32 v144, v144, v2
.LBB0_876:
	v_add_f32_e32 v2, 0, v15
	v_add_f32_e32 v2, v147, v2
	v_add_f32_e32 v2, v193, v2
	v_add_f32_e32 v2, v198, v2
	v_add_f32_e32 v2, v199, v2
	v_add_f32_e32 v2, v200, v2
	v_add_f32_e32 v2, v201, v2
	v_add_f32_e32 v2, v202, v2
	v_add_f32_e32 v2, v203, v2
	v_add_f32_e32 v2, v204, v2
	v_add_f32_e32 v2, v205, v2
	v_add_f32_e32 v2, v229, v2
	v_add_f32_e32 v2, v230, v2
	v_add_f32_e32 v2, v231, v2
	v_add_f32_e32 v2, v232, v2
	v_add_f32_e32 v2, v233, v2
	v_add_f32_e32 v112, v0, v2
	v_max3_f32 v0, v80, v81, v82
	v_max3_f32 v2, v83, v84, v85
	v_max3_f32 v3, v86, v87, v88
	v_max3_f32 v4, v89, v90, v91
	v_max3_f32 v5, v92, v93, v94
	v_max3_f32 v0, v0, v2, v3
	v_max3_f32 v4, v4, v5, v95
	v_max_f32_e32 v0, v0, v4
	v_mov_b32_e32 v2, v0
	s_nop 1
	v_permlane32_swap_b32_e32 v0, v2
	v_max_f32_e32 v2, v2, v2
	v_max_f32_e32 v0, v0, v0
	v_max_f32_e32 v0, v0, v2
	v_cmp_gt_f32_e32 vcc, v0, v189
	s_cbranch_vccz .LBB0_878
	v_max_f32_e32 v0, v0, v0
	v_max_f32_e32 v2, v189, v189
	v_max_f32_e32 v2, v2, v0
	v_sub_f32_e32 v0, v189, v2
	v_exp_f32_e32 v0, v0
	v_mov_b32_e32 v189, v2
	v_pk_mul_f32 v[46:47], v[46:47], v[0:1] op_sel_hi:[1,0]
	v_pk_mul_f32 v[44:45], v[44:45], v[0:1] op_sel_hi:[1,0]
	v_pk_mul_f32 v[42:43], v[42:43], v[0:1] op_sel_hi:[1,0]
	v_pk_mul_f32 v[40:41], v[40:41], v[0:1] op_sel_hi:[1,0]
	v_pk_mul_f32 v[38:39], v[38:39], v[0:1] op_sel_hi:[1,0]
	v_pk_mul_f32 v[36:37], v[36:37], v[0:1] op_sel_hi:[1,0]
	v_pk_mul_f32 v[34:35], v[34:35], v[0:1] op_sel_hi:[1,0]
	v_pk_mul_f32 v[32:33], v[32:33], v[0:1] op_sel_hi:[1,0]
	v_pk_mul_f32 v[30:31], v[30:31], v[0:1] op_sel_hi:[1,0]
	v_pk_mul_f32 v[28:29], v[28:29], v[0:1] op_sel_hi:[1,0]
	v_pk_mul_f32 v[26:27], v[26:27], v[0:1] op_sel_hi:[1,0]
	v_pk_mul_f32 v[24:25], v[24:25], v[0:1] op_sel_hi:[1,0]
	v_pk_mul_f32 v[22:23], v[22:23], v[0:1] op_sel_hi:[1,0]
	v_pk_mul_f32 v[20:21], v[20:21], v[0:1] op_sel_hi:[1,0]
	v_pk_mul_f32 v[18:19], v[18:19], v[0:1] op_sel_hi:[1,0]
	v_pk_mul_f32 v[16:17], v[16:17], v[0:1] op_sel_hi:[1,0]
	v_mul_f32_e32 v112, v112, v0

; template <int DK, bool NA> ...
;     ...
;             if (win) {
;               const int kc = kb * 32 + (i & 3) + 8 * (i >> 2) + 4 * h;
;               const bool vis = (unsigned)(kc - cs) < 16u;
;               const int idx = (kr - iw + 7) * 31 + (kc - jq + 15);
;               const float bv = biasL[vis ? idx : 0];
;               v = vis ? v + bv : -1e30f;
;             }
;           }
;           s[kb][i] = v; mx = fmaxf(mx, v);
.LBB0_967:
	s_waitcnt lgkmcnt(15)
	v_add_f32_e32 v49, v49, v173
	v_cndmask_b32_e64 v49, v222, v49, s[68:69]

; template <int DK, bool NA> ...
;     ...
;           float v = s[kb][i];
;           if (NA) {
;             if (win) {
;               const int kc = kb * 32 + (i & 3) + 8 * (i >> 2) + 4 * h;
;               const bool vis = (unsigned)(kc - cs) < 16u;
;               const int idx = (kr - iw + 7) * 31 + (kc - jq + 15);
;               const float bv = biasL[vis ? idx : 0];
;               v = vis ? v + bv : -1e30f;
;             }
;           }
;           s[kb][i] = v; mx = fmaxf(mx, v);
.LBB0_972:
	v_lshlrev_b32_e32 v172, 2, v132
	ds_read_b32 v173, v172 offset:37100
	ds_read_b32 v174, v172 offset:36864
	ds_read_b32 v175, v172 offset:36868
	ds_read_b32 v176, v172 offset:36872
	ds_read_b32 v177, v172 offset:36876
	ds_read_b32 v178, v172 offset:36896
	ds_read_b32 v179, v172 offset:36900
	ds_read_b32 v180, v172 offset:36904
	ds_read_b32 v181, v172 offset:36908
	ds_read_b32 v182, v172 offset:36928
	ds_read_b32 v183, v172 offset:36932
	ds_read_b32 v184, v172 offset:36936
	ds_read_b32 v185, v172 offset:36940
	ds_read_b32 v186, v172 offset:36960
	ds_read_b32 v187, v172 offset:36964
	ds_read_b32 v188, v172 offset:36968
	ds_read_b32 v189, v172 offset:36972
	ds_read_b32 v190, v172 offset:36992
	ds_read_b32 v191, v172 offset:36996
	ds_read_b32 v192, v172 offset:37000
	ds_read_b32 v193, v172 offset:37004
	ds_read_b32 v194, v172 offset:37024
	ds_read_b32 v195, v172 offset:37028
	ds_read_b32 v196, v172 offset:37032
	ds_read_b32 v197, v172 offset:37036
	ds_read_b32 v198, v172 offset:37056
	ds_read_b32 v199, v172 offset:37060
	ds_read_b32 v200, v172 offset:37064
	ds_read_b32 v201, v172 offset:37068
	ds_read_b32 v202, v172 offset:37088
	ds_read_b32 v203, v172 offset:37092
	ds_read_b32 v204, v172 offset:37096
	s_waitcnt lgkmcnt(15)
	v_add_f32_e32 v50, v50, v174
	v_cndmask_b32_e64 v50, v222, v50, s[72:73]
	s_or_b64 exec, exec, s[2:3]
	s_and_saveexec_b64 s[2:3], vcc
	s_cbranch_execz .LBB0_937
.LBB0_973:
	v_readlane_b32 s0, v254, 56
	v_readlane_b32 s1, v254, 57
	s_nop 1
	s_waitcnt lgkmcnt(15)
	v_add_f32_e32 v51, v51, v175
	v_cndmask_b32_e64 v51, v222, v51, s[0:1]
	s_or_b64 exec, exec, s[2:3]
	s_and_saveexec_b64 s[2:3], vcc
	s_cbranch_execz .LBB0_938
.LBB0_974:
	v_readlane_b32 s0, v254, 58
	v_readlane_b32 s1, v254, 59
	s_nop 1
	s_waitcnt lgkmcnt(15)
	v_add_f32_e32 v52, v52, v176
	v_cndmask_b32_e64 v52, v222, v52, s[0:1]
	s_or_b64 exec, exec, s[2:3]
	s_and_saveexec_b64 s[2:3], vcc
	s_cbranch_execz .LBB0_939
.LBB0_975:
	v_readlane_b32 s0, v254, 60
	v_readlane_b32 s1, v254, 61
	s_nop 1
	s_waitcnt lgkmcnt(15)
	v_add_f32_e32 v53, v53, v177
	v_cndmask_b32_e64 v53, v222, v53, s[0:1]
	s_or_b64 exec, exec, s[2:3]
	s_and_saveexec_b64 s[2:3], vcc
	s_cbranch_execz .LBB0_940
.LBB0_976:
	v_readlane_b32 s0, v254, 62
	v_readlane_b32 s1, v254, 63
	s_nop 1
	s_waitcnt lgkmcnt(15)
	v_add_f32_e32 v54, v54, v178
	v_cndmask_b32_e64 v54, v222, v54, s[0:1]
	s_or_b64 exec, exec, s[2:3]
	s_and_saveexec_b64 s[2:3], vcc
	s_cbranch_execz .LBB0_941
.LBB0_977:
	v_readlane_b32 s0, v255, 0
	v_readlane_b32 s1, v255, 1
	s_nop 1
	s_waitcnt lgkmcnt(15)
	v_add_f32_e32 v55, v55, v179
	v_cndmask_b32_e64 v55, v222, v55, s[0:1]
	s_or_b64 exec, exec, s[2:3]
	s_and_saveexec_b64 s[2:3], vcc
	s_cbranch_execz .LBB0_942
.LBB0_978:
	s_waitcnt lgkmcnt(15)
	v_add_f32_e32 v56, v56, v180
	v_cndmask_b32_e64 v56, v222, v56, s[16:17]
	s_or_b64 exec, exec, s[2:3]
	s_and_saveexec_b64 s[2:3], vcc
	s_cbranch_execz .LBB0_943
.LBB0_979:
	s_waitcnt lgkmcnt(15)
	v_add_f32_e32 v57, v57, v181
	v_cndmask_b32_e64 v57, v222, v57, s[18:19]
	s_or_b64 exec, exec, s[2:3]
	s_and_saveexec_b64 s[2:3], vcc
	s_cbranch_execz .LBB0_944
.LBB0_980:
	s_waitcnt lgkmcnt(15)
	v_add_f32_e32 v58, v58, v182
	v_cndmask_b32_e64 v58, v222, v58, s[20:21]
	s_or_b64 exec, exec, s[2:3]
	s_and_saveexec_b64 s[2:3], vcc
	s_cbranch_execz .LBB0_945
.LBB0_981:
	s_waitcnt lgkmcnt(15)
	v_add_f32_e32 v59, v59, v183
	v_cndmask_b32_e64 v59, v222, v59, s[22:23]
	s_or_b64 exec, exec, s[2:3]
	s_and_saveexec_b64 s[2:3], vcc
	s_cbranch_execz .LBB0_946
.LBB0_982:
	s_waitcnt lgkmcnt(15)
	v_add_f32_e32 v60, v60, v184
	v_cndmask_b32_e64 v60, v222, v60, s[24:25]
	s_or_b64 exec, exec, s[2:3]
	s_and_saveexec_b64 s[2:3], vcc
	s_cbranch_execz .LBB0_947
.LBB0_983:
	s_waitcnt lgkmcnt(15)
	v_add_f32_e32 v61, v61, v185
	v_cndmask_b32_e64 v61, v222, v61, s[26:27]
	s_or_b64 exec, exec, s[2:3]
	s_and_saveexec_b64 s[2:3], vcc
	s_cbranch_execz .LBB0_948
; template <int DK, bool NA> ...
;     ...
;           float v = s[kb][i];
;           if (NA) {
;             if (win) {
;               const int kc = kb * 32 + (i & 3) + 8 * (i >> 2) + 4 * h;
;               const bool vis = (unsigned)(kc - cs) < 16u;
;               const int idx = (kr - iw + 7) * 31 + (kc - jq + 15);
;               const float bv = biasL[vis ? idx : 0];
;               v = vis ? v + bv : -1e30f;
;             }
;           }
;           s[kb][i] = v; mx = fmaxf(mx, v);
.LBB0_984:
	s_waitcnt lgkmcnt(15)
	v_add_f32_e32 v62, v62, v186
	v_cndmask_b32_e64 v62, v222, v62, s[28:29]
	s_or_b64 exec, exec, s[2:3]
	s_and_saveexec_b64 s[2:3], vcc
	s_cbranch_execz .LBB0_949
.LBB0_985:
	s_waitcnt lgkmcnt(15)
	v_add_f32_e32 v63, v63, v187
	v_cndmask_b32_e64 v63, v222, v63, s[30:31]
	s_or_b64 exec, exec, s[2:3]
	s_and_saveexec_b64 s[2:3], vcc
	s_cbranch_execz .LBB0_950
.LBB0_986:
	s_waitcnt lgkmcnt(15)
	v_add_f32_e32 v64, v64, v188
	v_cndmask_b32_e64 v64, v222, v64, s[34:35]
	s_or_b64 exec, exec, s[2:3]
	s_and_saveexec_b64 s[2:3], vcc
	s_cbranch_execz .LBB0_951
.LBB0_987:
	s_waitcnt lgkmcnt(15)
	v_add_f32_e32 v65, v65, v189
	v_cndmask_b32_e64 v65, v222, v65, s[36:37]
	s_or_b64 exec, exec, s[2:3]
	s_and_saveexec_b64 s[2:3], vcc
	s_cbranch_execz .LBB0_952
.LBB0_988:
	s_waitcnt lgkmcnt(14)
	v_add_f32_e32 v34, v34, v190
	v_cndmask_b32_e64 v34, v222, v34, s[38:39]
	s_or_b64 exec, exec, s[2:3]
	s_and_saveexec_b64 s[2:3], vcc
	s_cbranch_execz .LBB0_953
.LBB0_989:
	s_waitcnt lgkmcnt(13)
	v_add_f32_e32 v35, v35, v191
	v_cndmask_b32_e64 v35, v222, v35, s[40:41]
	s_or_b64 exec, exec, s[2:3]
	s_and_saveexec_b64 s[2:3], vcc
	s_cbranch_execz .LBB0_954
.LBB0_990:
	s_waitcnt lgkmcnt(12)
	v_add_f32_e32 v36, v36, v192
	v_cndmask_b32_e64 v36, v222, v36, s[42:43]
	s_or_b64 exec, exec, s[2:3]
	s_and_saveexec_b64 s[2:3], vcc
	s_cbranch_execz .LBB0_955
.LBB0_991:
	s_waitcnt lgkmcnt(11)
	v_add_f32_e32 v37, v37, v193
	v_cndmask_b32_e64 v37, v222, v37, s[44:45]
	s_or_b64 exec, exec, s[2:3]
	s_and_saveexec_b64 s[2:3], vcc
	s_cbranch_execz .LBB0_956
.LBB0_992:
	s_waitcnt lgkmcnt(10)
	v_add_f32_e32 v38, v38, v194
	v_cndmask_b32_e64 v38, v222, v38, s[46:47]
	s_or_b64 exec, exec, s[2:3]
	s_and_saveexec_b64 s[2:3], vcc
	s_cbranch_execz .LBB0_957
.LBB0_993:
	s_waitcnt lgkmcnt(9)
	v_add_f32_e32 v39, v39, v195
	v_cndmask_b32_e64 v39, v222, v39, s[48:49]
	s_or_b64 exec, exec, s[2:3]
	s_and_saveexec_b64 s[2:3], vcc
	s_cbranch_execz .LBB0_958
.LBB0_994:
	s_waitcnt lgkmcnt(8)
	v_add_f32_e32 v40, v40, v196
	v_cndmask_b32_e64 v40, v222, v40, s[50:51]
	s_or_b64 exec, exec, s[2:3]
	s_and_saveexec_b64 s[2:3], vcc
	s_cbranch_execz .LBB0_959
.LBB0_995:
	s_waitcnt lgkmcnt(7)
	v_add_f32_e32 v41, v41, v197
	v_cndmask_b32_e64 v41, v222, v41, s[52:53]
	s_or_b64 exec, exec, s[2:3]
	s_and_saveexec_b64 s[2:3], vcc
	s_cbranch_execz .LBB0_960
.LBB0_996:
	s_waitcnt lgkmcnt(6)
	v_add_f32_e32 v42, v42, v198
	v_cndmask_b32_e64 v42, v222, v42, s[54:55]
	s_or_b64 exec, exec, s[2:3]
	s_and_saveexec_b64 s[2:3], vcc
	s_cbranch_execz .LBB0_961
.LBB0_997:
	s_waitcnt lgkmcnt(5)
	v_add_f32_e32 v43, v43, v199
	v_cndmask_b32_e64 v43, v222, v43, s[56:57]
	s_or_b64 exec, exec, s[2:3]
	s_and_saveexec_b64 s[2:3], vcc
	s_cbranch_execz .LBB0_962
.LBB0_998:
	s_waitcnt lgkmcnt(4)
	v_add_f32_e32 v44, v44, v200
	v_cndmask_b32_e64 v44, v222, v44, s[58:59]
	s_or_b64 exec, exec, s[2:3]
	s_and_saveexec_b64 s[2:3], vcc
	s_cbranch_execz .LBB0_963
.LBB0_999:
	s_waitcnt lgkmcnt(3)
	v_add_f32_e32 v45, v45, v201
	v_cndmask_b32_e64 v45, v222, v45, s[60:61]
	s_or_b64 exec, exec, s[2:3]
	s_and_saveexec_b64 s[2:3], vcc
	s_cbranch_execz .LBB0_964
.LBB0_1000:
	s_waitcnt lgkmcnt(2)
	v_add_f32_e32 v46, v46, v202
	v_cndmask_b32_e64 v46, v222, v46, s[62:63]
	s_or_b64 exec, exec, s[2:3]
	s_and_saveexec_b64 s[2:3], vcc
	s_cbranch_execz .LBB0_965
.LBB0_1001:
	s_waitcnt lgkmcnt(1)
	v_add_f32_e32 v47, v47, v203
	v_cndmask_b32_e64 v47, v222, v47, s[64:65]
	s_or_b64 exec, exec, s[2:3]
	s_and_saveexec_b64 s[2:3], vcc
	s_cbranch_execz .LBB0_966
.LBB0_1002:
	s_waitcnt lgkmcnt(0)
	v_add_f32_e32 v48, v48, v204
	v_cndmask_b32_e64 v48, v222, v48, s[66:67]
	s_or_b64 exec, exec, s[2:3]
	s_and_saveexec_b64 s[2:3], vcc
	s_cbranch_execnz .LBB0_967
	s_branch .LBB0_968
